# rowwise modulation-vector setup: loads batched (one wait instead of three per column pair)
# baseline (speedup 1.0000x reference)
; __device__ __forceinline__ void rowwise_phase(const Args& a, LAS unsigned char* lds, bool from_partials, bool has_y, bool has_h, bool xin_bf, int xout_mode, ...
;     ...
;         for (int col = tid; col < DM; col += 512) {
;             if (from_partials) {
;                 if (has_y) vec[col] = mod_val(a, l_y, b, gate_idx, col) * g_post[col];
;                 if (has_h) { vec[DM + col] = g_pre[col] * (1.0f + mod_val(a, l_h, b, scale_idx, col)); vec[2 * DM + col] = mod_val(a, l_h, b, shift_idx, col); }
;             } else {
;                 if (has_y) vec[col] = mod_fin(a, l_y, b, gate_idx, col) * g_post[col];
;                 if (has_h) { vec[DM + col] = g_pre[col] * (1.0f + mod_fin(a, l_h, b, scale_idx, col)); vec[2 * DM + col] = mod_fin(a, l_h, b, shift_idx, col); }
;             }
;         }
.LBB0_508:
	v_ashrrev_i32_e32 v19, 31, v9
	v_mov_b32_e32 v18, v9
	v_ashrrev_i32_e32 v21, 31, v8
	v_mov_b32_e32 v20, v8
	v_lshlrev_b64 v[20:21], 2, v[20:21]
	v_lshlrev_b64 v[18:19], 2, v[18:19]
	v_lshl_add_u64 v[22:23], s[54:55], 0, v[20:21]
	v_lshl_add_u64 v[24:25], s[54:55], 0, v[18:19]
	global_load_dword v208, v[22:23], off
	global_load_dword v209, v[24:25], off
	v_lshl_add_u64 v[22:23], s[48:49], 0, v[20:21]
	v_lshl_add_u64 v[24:25], s[48:49], 0, v[18:19]
	global_load_dword v210, v[22:23], off
	global_load_dword v211, v[24:25], off
	v_lshl_add_u64 v[22:23], s[50:51], 0, v[20:21]
	v_lshl_add_u64 v[24:25], s[50:51], 0, v[18:19]
	global_load_dword v212, v[22:23], off
	global_load_dword v213, v[24:25], off
	v_lshl_add_u64 v[22:23], s[56:57], 0, v[20:21]
	v_lshl_add_u64 v[24:25], s[56:57], 0, v[18:19]
	global_load_dword v214, v[22:23], off
	global_load_dword v215, v[24:25], off
	v_lshl_add_u64 v[22:23], s[58:59], 0, v[20:21]
	v_lshl_add_u64 v[24:25], s[58:59], 0, v[18:19]
	global_load_dword v216, v[22:23], off
	global_load_dword v217, v[24:25], off
	v_add_u32_e32 v10, -2, v10
	v_add_u32_e32 v17, 0x1000, v11
	v_cmp_eq_u32_e32 vcc, 0, v10
	v_add_u32_e32 v9, 0x400, v9
	v_add_u32_e32 v8, 0x400, v8
	s_or_b64 s[60:61], vcc, s[60:61]
	s_waitcnt vmcnt(0)
	v_pk_mul_f32 v[208:209], v[208:209], v[210:211]
	ds_write2st64_b32 v11, v208, v209 offset1:8
	v_pk_add_f32 v[214:215], v[214:215], 1.0 op_sel_hi:[1,0]
	s_nop 0
	v_pk_mul_f32 v[212:213], v[212:213], v[214:215]
	ds_write2st64_b32 v11, v212, v213 offset0:16 offset1:24
	ds_write2st64_b32 v11, v216, v217 offset0:32 offset1:40
	v_mov_b32_e32 v11, v17
	s_andn2_b64 exec, exec, s[60:61]
	s_cbranch_execnz .LBB0_508
	s_or_b64 exec, exec, s[60:61]
	s_mov_b64 s[16:17], 0
	s_and_saveexec_b64 s[54:55], s[44:45]
	s_mov_b64 s[16:17], exec
	v_lshlrev_b32_e32 v9, 2, v15
	s_or_b64 exec, exec, s[54:55]
	s_orn2_b64 s[16:17], s[16:17], exec
	v_mov_b32_e32 v8, v15

; __device__ __forceinline__ void rowwise_phase(const Args& a, LAS unsigned char* lds, bool from_partials, bool has_y, bool has_h, bool xin_bf, int xout_mode, ...
;     ...
;         for (int col = tid; col < DM; col += 512) {
;             if (from_partials) {
;                 if (has_y) vec[col] = mod_val(a, l_y, b, gate_idx, col) * g_post[col];
;                 if (has_h) { vec[DM + col] = g_pre[col] * (1.0f + mod_val(a, l_h, b, scale_idx, col)); vec[2 * DM + col] = mod_val(a, l_h, b, shift_idx, col); }
;             } else {
;                 if (has_y) vec[col] = mod_fin(a, l_y, b, gate_idx, col) * g_post[col];
;                 if (has_h) { vec[DM + col] = g_pre[col] * (1.0f + mod_fin(a, l_h, b, scale_idx, col)); vec[2 * DM + col] = mod_fin(a, l_h, b, shift_idx, col); }
;             }
;         }
.LBB0_722:
	global_load_dword v11, v[2:3], off
	global_load_dword v12, v[8:9], off
	s_andn2_b64 vcc, exec, s[18:19]
	s_cbranch_vccnz .Lend_vec_nomore
	global_load_dword v208, v[6:7], off
	global_load_dword v209, v[4:5], off
	global_load_dword v210, v[4:5], off offset:-4096
	s_waitcnt vmcnt(3)
	v_mul_f32_e32 v11, v11, v12
	ds_write_b32 v0, v11
	s_waitcnt vmcnt(0)
	v_add_f32_e32 v209, 1.0, v209
	v_mul_f32_e32 v208, v208, v209
	ds_write2st64_b32 v0, v208, v210 offset0:16 offset1:32
	s_branch .LBB0_721
.Lend_vec_nomore:
	s_waitcnt vmcnt(0)
	v_mul_f32_e32 v11, v11, v12
	ds_write_b32 v0, v11
	s_branch .LBB0_721
